# v80 + sc1 write-through on the final out stores (P12), no dirty L2 lines left at kernel end
# speedup vs baseline: 1.0376x; 1.0014x over previous
; __device__ __forceinline__ float row_rstd(const float* slots, int row) {
;     const unsigned long long* sp = (const unsigned long long*)(slots + (size_t)row * 8); float t = 0.f;
; #pragma unroll
;     for (int q = 0; q < 4; ++q) { const unsigned long long w = __hip_atomic_load(sp + q, __ATOMIC_RELAXED, __HIP_MEMORY_SCOPE_AGENT); t += __uint_as_float((unsigned)w) + __uint_as_float((unsigned)(w >> 32)); }
;     return rsqrtf(t * (1.0f / DM) + EPS);
; __global__ void __launch_bounds__(NTHR, 2) fwd_kernel(Args a) {
;     ...
;         { const int wid2 = __builtin_amdgcn_readfirstlane(tid2 >> 6), colg = u.pn * BM + 4 * (tid2 & 63);
;           const f32x4 gf = *(const f32x4*)(a.in[I_GF] + colg);
; #pragma unroll
;           for (int ai = 0; ai < 2; ++ai)
; #pragma unroll
;               for (int j = 0; j < 16; ++j) { const int row = u.pm * BM + ai * HALF + wid2 * 16 + j; const float rstd = row_rstd(slots2, row);
;                   *(f32x4*)(out + (size_t)row * DM + colg) = xr[ai][j] * rstd * gf; }
.LBB0_2009:
	s_or_b64 exec, exec, s[0:1]
	s_waitcnt lgkmcnt(0)
	s_barrier
	v_readfirstlane_b32 s0, v189
	s_ashr_i32 s0, s0, 2
	v_lshlrev_b32_e32 v0, 2, v189
	s_and_b32 s0, s0, -16
	v_and_b32_e32 v0, 0xfc, v0
	s_add_i32 s0, s0, s46
	v_or_b32_e32 v0, s45, v0
	v_ashrrev_i32_e32 v1, 31, v0
	v_lshlrev_b64 v[64:65], 2, v[0:1]
	v_lshl_add_u64 v[0:1], s[62:63], 0, v[64:65]
	global_load_dwordx4 v[0:3], v[0:1], off
	v_lshl_add_u64 v[64:65], s[64:65], 0, v[64:65]
	s_mov_b32 s4, s33
	s_mov_b32 s5, s44
	v_and_b32_e32 v144, 31, v189
	v_and_b32_e32 v145, 15, v144
	v_lshrrev_b32_e32 v144, 4, v144
	v_lshl_add_u32 v145, v144, 7, v145
	v_add_u32_e32 v145, s0, v145
	v_lshlrev_b32_e32 v66, 5, v145
	global_load_dwordx4 v[136:139], v66, s[4:5] sc1
	global_load_dwordx4 v[140:143], v66, s[4:5] offset:16 sc1
	v_mov_b32_e32 v67, 0x358637bd
	s_mov_b32 s2, 0x800000
	s_waitcnt vmcnt(0)
	v_add_f32_e32 v136, v136, v137
	v_add_f32_e32 v137, v138, v139
	v_add_f32_e32 v136, 0, v136
	v_add_f32_e32 v138, v140, v141
	v_add_f32_e32 v136, v136, v137
	v_add_f32_e32 v139, v142, v143
	v_add_f32_e32 v136, v136, v138
	v_add_f32_e32 v136, v136, v139
	v_fmamk_f32 v136, v136, 0x3a000000, v67
	v_mul_f32_e32 v137, 0x4b800000, v136
	v_cmp_gt_f32_e32 vcc, s2, v136
	s_nop 1
	v_cndmask_b32_e32 v136, v136, v137, vcc
	v_rsq_f32_e32 v136, v136
	s_nop 0
	v_mul_f32_e32 v137, 0x45800000, v136
	v_cndmask_b32_e32 v66, v136, v137, vcc
	s_mov_b32 s7, 0
	v_readlane_b32 s4, v66, 0
	s_add_i32 s6, s0, 0
	s_lshl_b32 s6, s6, 13
	v_lshl_add_u64 v[144:145], v[64:65], 0, s[6:7]
	v_pk_mul_f32 v[136:137], v[72:73], s[4:5] op_sel_hi:[1,0]
	v_pk_mul_f32 v[138:139], v[68:69], s[4:5] op_sel_hi:[1,0]
	v_pk_mul_f32 v[136:137], v[0:1], v[136:137]
	v_pk_mul_f32 v[138:139], v[2:3], v[138:139]
	global_store_dwordx4 v[144:145], v[136:139], off sc1
	v_readlane_b32 s4, v66, 1
	s_add_i32 s6, s0, 1
	s_lshl_b32 s6, s6, 13
	v_lshl_add_u64 v[146:147], v[64:65], 0, s[6:7]
	v_pk_mul_f32 v[140:141], v[76:77], s[4:5] op_sel_hi:[1,0]
	v_pk_mul_f32 v[142:143], v[70:71], s[4:5] op_sel_hi:[1,0]
	v_pk_mul_f32 v[140:141], v[0:1], v[140:141]
	v_pk_mul_f32 v[142:143], v[2:3], v[142:143]
	global_store_dwordx4 v[146:147], v[140:143], off sc1
	v_readlane_b32 s4, v66, 2
	s_add_i32 s6, s0, 2
	s_lshl_b32 s6, s6, 13
	v_lshl_add_u64 v[144:145], v[64:65], 0, s[6:7]
	v_pk_mul_f32 v[136:137], v[80:81], s[4:5] op_sel_hi:[1,0]
	v_pk_mul_f32 v[138:139], v[74:75], s[4:5] op_sel_hi:[1,0]
	v_pk_mul_f32 v[136:137], v[0:1], v[136:137]
	v_pk_mul_f32 v[138:139], v[2:3], v[138:139]
	global_store_dwordx4 v[144:145], v[136:139], off sc1
	v_readlane_b32 s4, v66, 3
	s_add_i32 s6, s0, 3
	s_lshl_b32 s6, s6, 13
	v_lshl_add_u64 v[146:147], v[64:65], 0, s[6:7]
	v_pk_mul_f32 v[140:141], v[86:87], s[4:5] op_sel_hi:[1,0]
	v_pk_mul_f32 v[142:143], v[78:79], s[4:5] op_sel_hi:[1,0]
	v_pk_mul_f32 v[140:141], v[0:1], v[140:141]
	v_pk_mul_f32 v[142:143], v[2:3], v[142:143]
	global_store_dwordx4 v[146:147], v[140:143], off sc1
	v_readlane_b32 s4, v66, 4
	s_add_i32 s6, s0, 4
	s_lshl_b32 s6, s6, 13
	v_lshl_add_u64 v[144:145], v[64:65], 0, s[6:7]
	v_pk_mul_f32 v[136:137], v[90:91], s[4:5] op_sel_hi:[1,0]
	v_pk_mul_f32 v[138:139], v[82:83], s[4:5] op_sel_hi:[1,0]
	v_pk_mul_f32 v[136:137], v[0:1], v[136:137]
	v_pk_mul_f32 v[138:139], v[2:3], v[138:139]
	global_store_dwordx4 v[144:145], v[136:139], off sc1
	v_readlane_b32 s4, v66, 5
	s_add_i32 s6, s0, 5
	s_lshl_b32 s6, s6, 13
	v_lshl_add_u64 v[146:147], v[64:65], 0, s[6:7]
	v_pk_mul_f32 v[140:141], v[94:95], s[4:5] op_sel_hi:[1,0]
	v_pk_mul_f32 v[142:143], v[84:85], s[4:5] op_sel_hi:[1,0]
	v_pk_mul_f32 v[140:141], v[0:1], v[140:141]
	v_pk_mul_f32 v[142:143], v[2:3], v[142:143]
	global_store_dwordx4 v[146:147], v[140:143], off sc1
	v_readlane_b32 s4, v66, 6
	s_add_i32 s6, s0, 6
	s_lshl_b32 s6, s6, 13
	v_lshl_add_u64 v[144:145], v[64:65], 0, s[6:7]
	v_pk_mul_f32 v[136:137], v[98:99], s[4:5] op_sel_hi:[1,0]
	v_pk_mul_f32 v[138:139], v[88:89], s[4:5] op_sel_hi:[1,0]
	v_pk_mul_f32 v[136:137], v[0:1], v[136:137]
	v_pk_mul_f32 v[138:139], v[2:3], v[138:139]
	global_store_dwordx4 v[144:145], v[136:139], off sc1
	v_readlane_b32 s4, v66, 7
	s_add_i32 s6, s0, 7
	s_lshl_b32 s6, s6, 13
	v_lshl_add_u64 v[146:147], v[64:65], 0, s[6:7]
	v_pk_mul_f32 v[140:141], v[102:103], s[4:5] op_sel_hi:[1,0]
	v_pk_mul_f32 v[142:143], v[92:93], s[4:5] op_sel_hi:[1,0]
	v_pk_mul_f32 v[140:141], v[0:1], v[140:141]
	v_pk_mul_f32 v[142:143], v[2:3], v[142:143]
	global_store_dwordx4 v[146:147], v[140:143], off sc1
	v_readlane_b32 s4, v66, 8
	s_add_i32 s6, s0, 8
	s_lshl_b32 s6, s6, 13
	v_lshl_add_u64 v[144:145], v[64:65], 0, s[6:7]
	v_pk_mul_f32 v[136:137], v[106:107], s[4:5] op_sel_hi:[1,0]
	v_pk_mul_f32 v[138:139], v[96:97], s[4:5] op_sel_hi:[1,0]
	v_pk_mul_f32 v[136:137], v[0:1], v[136:137]
	v_pk_mul_f32 v[138:139], v[2:3], v[138:139]
	global_store_dwordx4 v[144:145], v[136:139], off sc1
	v_readlane_b32 s4, v66, 9
	s_add_i32 s6, s0, 9
	s_lshl_b32 s6, s6, 13
	v_lshl_add_u64 v[146:147], v[64:65], 0, s[6:7]
	v_pk_mul_f32 v[140:141], v[110:111], s[4:5] op_sel_hi:[1,0]
	v_pk_mul_f32 v[142:143], v[100:101], s[4:5] op_sel_hi:[1,0]
	v_pk_mul_f32 v[140:141], v[0:1], v[140:141]
	v_pk_mul_f32 v[142:143], v[2:3], v[142:143]
	global_store_dwordx4 v[146:147], v[140:143], off sc1
	v_readlane_b32 s4, v66, 10
	s_add_i32 s6, s0, 10
	s_lshl_b32 s6, s6, 13
	v_lshl_add_u64 v[144:145], v[64:65], 0, s[6:7]
	v_pk_mul_f32 v[136:137], v[114:115], s[4:5] op_sel_hi:[1,0]
	v_pk_mul_f32 v[138:139], v[104:105], s[4:5] op_sel_hi:[1,0]
	v_pk_mul_f32 v[136:137], v[0:1], v[136:137]
	v_pk_mul_f32 v[138:139], v[2:3], v[138:139]
	global_store_dwordx4 v[144:145], v[136:139], off sc1
	v_readlane_b32 s4, v66, 11
; __global__ void __launch_bounds__(NTHR, 2) fwd_kernel(Args a) {
;     ...
;           for (int ai = 0; ai < 2; ++ai)
; #pragma unroll
;               for (int j = 0; j < 16; ++j) { const int row = u.pm * BM + ai * HALF + wid2 * 16 + j; const float rstd = row_rstd(slots2, row);
;                   *(f32x4*)(out + (size_t)row * DM + colg) = xr[ai][j] * rstd * gf; }
	s_add_i32 s6, s0, 11
	s_lshl_b32 s6, s6, 13
	v_lshl_add_u64 v[146:147], v[64:65], 0, s[6:7]
	v_pk_mul_f32 v[140:141], v[118:119], s[4:5] op_sel_hi:[1,0]
	v_pk_mul_f32 v[142:143], v[108:109], s[4:5] op_sel_hi:[1,0]
	v_pk_mul_f32 v[140:141], v[0:1], v[140:141]
	v_pk_mul_f32 v[142:143], v[2:3], v[142:143]
	global_store_dwordx4 v[146:147], v[140:143], off sc1
	v_readlane_b32 s4, v66, 12
	s_add_i32 s6, s0, 12
	s_lshl_b32 s6, s6, 13
	v_lshl_add_u64 v[144:145], v[64:65], 0, s[6:7]
	v_pk_mul_f32 v[136:137], v[122:123], s[4:5] op_sel_hi:[1,0]
	v_pk_mul_f32 v[138:139], v[112:113], s[4:5] op_sel_hi:[1,0]
	v_pk_mul_f32 v[136:137], v[0:1], v[136:137]
	v_pk_mul_f32 v[138:139], v[2:3], v[138:139]
	global_store_dwordx4 v[144:145], v[136:139], off sc1
	v_readlane_b32 s4, v66, 13
	s_add_i32 s6, s0, 13
	s_lshl_b32 s6, s6, 13
	v_lshl_add_u64 v[146:147], v[64:65], 0, s[6:7]
	v_pk_mul_f32 v[140:141], v[126:127], s[4:5] op_sel_hi:[1,0]
	v_pk_mul_f32 v[142:143], v[116:117], s[4:5] op_sel_hi:[1,0]
	v_pk_mul_f32 v[140:141], v[0:1], v[140:141]
	v_pk_mul_f32 v[142:143], v[2:3], v[142:143]
	global_store_dwordx4 v[146:147], v[140:143], off sc1
	v_readlane_b32 s4, v66, 14
	s_add_i32 s6, s0, 14
	s_lshl_b32 s6, s6, 13
	v_lshl_add_u64 v[144:145], v[64:65], 0, s[6:7]
	v_pk_mul_f32 v[136:137], v[128:129], s[4:5] op_sel_hi:[1,0]
	v_pk_mul_f32 v[138:139], v[120:121], s[4:5] op_sel_hi:[1,0]
	v_pk_mul_f32 v[136:137], v[0:1], v[136:137]
	v_pk_mul_f32 v[138:139], v[2:3], v[138:139]
	global_store_dwordx4 v[144:145], v[136:139], off sc1
	v_readlane_b32 s4, v66, 15
	s_add_i32 s6, s0, 15
	s_lshl_b32 s6, s6, 13
	v_lshl_add_u64 v[146:147], v[64:65], 0, s[6:7]
	v_pk_mul_f32 v[140:141], v[130:131], s[4:5] op_sel_hi:[1,0]
	v_pk_mul_f32 v[142:143], v[124:125], s[4:5] op_sel_hi:[1,0]
	v_pk_mul_f32 v[140:141], v[0:1], v[140:141]
	v_pk_mul_f32 v[142:143], v[2:3], v[142:143]
	global_store_dwordx4 v[146:147], v[140:143], off sc1
	v_readlane_b32 s4, v66, 16
	s_add_i32 s6, s0, 128
	s_lshl_b32 s6, s6, 13
	v_lshl_add_u64 v[144:145], v[64:65], 0, s[6:7]
	v_pk_mul_f32 v[136:137], v[134:135], s[4:5] op_sel_hi:[1,0]
	v_pk_mul_f32 v[138:139], v[132:133], s[4:5] op_sel_hi:[1,0]
	v_pk_mul_f32 v[136:137], v[0:1], v[136:137]
	v_pk_mul_f32 v[138:139], v[2:3], v[138:139]
	global_store_dwordx4 v[144:145], v[136:139], off sc1
	v_readlane_b32 s4, v66, 17
	s_add_i32 s6, s0, 129
	s_lshl_b32 s6, s6, 13
	v_lshl_add_u64 v[146:147], v[64:65], 0, s[6:7]
	v_pk_mul_f32 v[140:141], v[62:63], s[4:5] op_sel_hi:[1,0]
	v_pk_mul_f32 v[142:143], v[60:61], s[4:5] op_sel_hi:[1,0]
	v_pk_mul_f32 v[140:141], v[0:1], v[140:141]
	v_pk_mul_f32 v[142:143], v[2:3], v[142:143]
	global_store_dwordx4 v[146:147], v[140:143], off sc1
	v_readlane_b32 s4, v66, 18
	s_add_i32 s6, s0, 130
	s_lshl_b32 s6, s6, 13
	v_lshl_add_u64 v[144:145], v[64:65], 0, s[6:7]
	v_pk_mul_f32 v[136:137], v[58:59], s[4:5] op_sel_hi:[1,0]
	v_pk_mul_f32 v[138:139], v[56:57], s[4:5] op_sel_hi:[1,0]
	v_pk_mul_f32 v[136:137], v[0:1], v[136:137]
	v_pk_mul_f32 v[138:139], v[2:3], v[138:139]
	global_store_dwordx4 v[144:145], v[136:139], off sc1
	v_readlane_b32 s4, v66, 19
	s_add_i32 s6, s0, 131
	s_lshl_b32 s6, s6, 13
	v_lshl_add_u64 v[146:147], v[64:65], 0, s[6:7]
	v_pk_mul_f32 v[140:141], v[54:55], s[4:5] op_sel_hi:[1,0]
	v_pk_mul_f32 v[142:143], v[52:53], s[4:5] op_sel_hi:[1,0]
	v_pk_mul_f32 v[140:141], v[0:1], v[140:141]
	v_pk_mul_f32 v[142:143], v[2:3], v[142:143]
	global_store_dwordx4 v[146:147], v[140:143], off sc1
	v_readlane_b32 s4, v66, 20
	s_add_i32 s6, s0, 132
	s_lshl_b32 s6, s6, 13
	v_lshl_add_u64 v[144:145], v[64:65], 0, s[6:7]
	v_pk_mul_f32 v[136:137], v[50:51], s[4:5] op_sel_hi:[1,0]
	v_pk_mul_f32 v[138:139], v[48:49], s[4:5] op_sel_hi:[1,0]
	v_pk_mul_f32 v[136:137], v[0:1], v[136:137]
	v_pk_mul_f32 v[138:139], v[2:3], v[138:139]
	global_store_dwordx4 v[144:145], v[136:139], off sc1
	v_readlane_b32 s4, v66, 21
	s_add_i32 s6, s0, 133
	s_lshl_b32 s6, s6, 13
	v_lshl_add_u64 v[146:147], v[64:65], 0, s[6:7]
	v_pk_mul_f32 v[140:141], v[46:47], s[4:5] op_sel_hi:[1,0]
; __global__ void __launch_bounds__(NTHR, 2) fwd_kernel(Args a) {
;     ...
;           for (int ai = 0; ai < 2; ++ai)
; #pragma unroll
;               for (int j = 0; j < 16; ++j) { const int row = u.pm * BM + ai * HALF + wid2 * 16 + j; const float rstd = row_rstd(slots2, row);
;                   *(f32x4*)(out + (size_t)row * DM + colg) = xr[ai][j] * rstd * gf; }
	v_pk_mul_f32 v[142:143], v[44:45], s[4:5] op_sel_hi:[1,0]
	v_pk_mul_f32 v[140:141], v[0:1], v[140:141]
	v_pk_mul_f32 v[142:143], v[2:3], v[142:143]
	global_store_dwordx4 v[146:147], v[140:143], off sc1
	v_readlane_b32 s4, v66, 22
	s_add_i32 s6, s0, 134
	s_lshl_b32 s6, s6, 13
	v_lshl_add_u64 v[144:145], v[64:65], 0, s[6:7]
	v_pk_mul_f32 v[136:137], v[42:43], s[4:5] op_sel_hi:[1,0]
	v_pk_mul_f32 v[138:139], v[40:41], s[4:5] op_sel_hi:[1,0]
	v_pk_mul_f32 v[136:137], v[0:1], v[136:137]
	v_pk_mul_f32 v[138:139], v[2:3], v[138:139]
	global_store_dwordx4 v[144:145], v[136:139], off sc1
	v_readlane_b32 s4, v66, 23
	s_add_i32 s6, s0, 135
	s_lshl_b32 s6, s6, 13
	v_lshl_add_u64 v[146:147], v[64:65], 0, s[6:7]
	v_pk_mul_f32 v[140:141], v[38:39], s[4:5] op_sel_hi:[1,0]
	v_pk_mul_f32 v[142:143], v[36:37], s[4:5] op_sel_hi:[1,0]
	v_pk_mul_f32 v[140:141], v[0:1], v[140:141]
	v_pk_mul_f32 v[142:143], v[2:3], v[142:143]
	global_store_dwordx4 v[146:147], v[140:143], off sc1
	v_readlane_b32 s4, v66, 24
	s_add_i32 s6, s0, 136
	s_lshl_b32 s6, s6, 13
	v_lshl_add_u64 v[144:145], v[64:65], 0, s[6:7]
	v_pk_mul_f32 v[136:137], v[34:35], s[4:5] op_sel_hi:[1,0]
	v_pk_mul_f32 v[138:139], v[32:33], s[4:5] op_sel_hi:[1,0]
	v_pk_mul_f32 v[136:137], v[0:1], v[136:137]
	v_pk_mul_f32 v[138:139], v[2:3], v[138:139]
	global_store_dwordx4 v[144:145], v[136:139], off sc1
	v_readlane_b32 s4, v66, 25
	s_add_i32 s6, s0, 137
	s_lshl_b32 s6, s6, 13
	v_lshl_add_u64 v[146:147], v[64:65], 0, s[6:7]
	v_pk_mul_f32 v[140:141], v[30:31], s[4:5] op_sel_hi:[1,0]
	v_pk_mul_f32 v[142:143], v[28:29], s[4:5] op_sel_hi:[1,0]
	v_pk_mul_f32 v[140:141], v[0:1], v[140:141]
	v_pk_mul_f32 v[142:143], v[2:3], v[142:143]
	global_store_dwordx4 v[146:147], v[140:143], off sc1
	v_readlane_b32 s4, v66, 26
	s_add_i32 s6, s0, 138
	s_lshl_b32 s6, s6, 13
	v_lshl_add_u64 v[144:145], v[64:65], 0, s[6:7]
	v_pk_mul_f32 v[136:137], v[26:27], s[4:5] op_sel_hi:[1,0]
	v_pk_mul_f32 v[138:139], v[24:25], s[4:5] op_sel_hi:[1,0]
	v_pk_mul_f32 v[136:137], v[0:1], v[136:137]
	v_pk_mul_f32 v[138:139], v[2:3], v[138:139]
	global_store_dwordx4 v[144:145], v[136:139], off sc1
	v_readlane_b32 s4, v66, 27
	s_add_i32 s6, s0, 139
	s_lshl_b32 s6, s6, 13
	v_lshl_add_u64 v[146:147], v[64:65], 0, s[6:7]
	v_pk_mul_f32 v[140:141], v[22:23], s[4:5] op_sel_hi:[1,0]
	v_pk_mul_f32 v[142:143], v[20:21], s[4:5] op_sel_hi:[1,0]
	v_pk_mul_f32 v[140:141], v[0:1], v[140:141]
	v_pk_mul_f32 v[142:143], v[2:3], v[142:143]
	global_store_dwordx4 v[146:147], v[140:143], off sc1
	v_readlane_b32 s4, v66, 28
	s_add_i32 s6, s0, 140
	s_lshl_b32 s6, s6, 13
	v_lshl_add_u64 v[144:145], v[64:65], 0, s[6:7]
	v_pk_mul_f32 v[136:137], v[18:19], s[4:5] op_sel_hi:[1,0]
	v_pk_mul_f32 v[138:139], v[14:15], s[4:5] op_sel_hi:[1,0]
	v_pk_mul_f32 v[136:137], v[0:1], v[136:137]
	v_pk_mul_f32 v[138:139], v[2:3], v[138:139]
	global_store_dwordx4 v[144:145], v[136:139], off sc1
	v_readlane_b32 s4, v66, 29
	s_add_i32 s6, s0, 141
	s_lshl_b32 s6, s6, 13
	v_lshl_add_u64 v[146:147], v[64:65], 0, s[6:7]
	v_pk_mul_f32 v[140:141], v[12:13], s[4:5] op_sel_hi:[1,0]
	v_pk_mul_f32 v[142:143], v[8:9], s[4:5] op_sel_hi:[1,0]
	v_pk_mul_f32 v[140:141], v[0:1], v[140:141]
	v_pk_mul_f32 v[142:143], v[2:3], v[142:143]
	global_store_dwordx4 v[146:147], v[140:143], off sc1
	v_readlane_b32 s4, v66, 30
	s_add_i32 s6, s0, 142
	s_lshl_b32 s6, s6, 13
	v_lshl_add_u64 v[144:145], v[64:65], 0, s[6:7]
	v_pk_mul_f32 v[136:137], v[6:7], s[4:5] op_sel_hi:[1,0]
	v_pk_mul_f32 v[138:139], v[4:5], s[4:5] op_sel_hi:[1,0]
	v_pk_mul_f32 v[136:137], v[0:1], v[136:137]
	v_pk_mul_f32 v[138:139], v[2:3], v[138:139]
	global_store_dwordx4 v[144:145], v[136:139], off sc1
	v_readlane_b32 s4, v66, 31
	s_add_i32 s6, s0, 143
	s_lshl_b32 s6, s6, 13
	v_lshl_add_u64 v[146:147], v[64:65], 0, s[6:7]
	v_pk_mul_f32 v[140:141], v[16:17], s[4:5] op_sel_hi:[1,0]
	v_pk_mul_f32 v[142:143], v[10:11], s[4:5] op_sel_hi:[1,0]
	v_pk_mul_f32 v[140:141], v[0:1], v[140:141]
	v_pk_mul_f32 v[142:143], v[2:3], v[142:143]
	global_store_dwordx4 v[146:147], v[140:143], off sc1
	s_endpgm
